# o1+idx relu canonicalize removal (64 VALU/16 MFMA), scan ds_read2_b64 split into conflict-free ds_read_b64 + tr-read offsets folded, attention mask bfe+and instead of and+cmp+cndmask
# baseline (speedup 1.0000x reference)
.LBB0_1414:
	ds_read_b128 v[122:125], v164
	ds_read_b128 v[114:117], v164 offset:32
	ds_read_b128 v[106:109], v164 offset:64
	ds_read_b128 v[98:101], v164 offset:96
	ds_read_b128 v[126:129], v164 offset:128
	ds_read_b128 v[118:121], v164 offset:160
	ds_read_b128 v[110:113], v164 offset:192
	ds_read_b128 v[102:105], v164 offset:224
	v_add_u32_e32 v2, s4, v134
	ds_read_b64 v[152:153], v2
	s_waitcnt vmcnt(7) lgkmcnt(8)
	v_mfma_f32_32x32x16_bf16 v[2:17], v[50:53], v[122:125], 0
	s_add_i32 s4, s4, 8
	v_add_u32_e32 v164, 0x100, v164
	s_cmp_eq_u32 s4, 64
	s_waitcnt lgkmcnt(4)
	v_mfma_f32_32x32x16_bf16 v[18:33], v[50:53], v[126:129], 0
	s_waitcnt vmcnt(6)
	v_mfma_f32_32x32x16_bf16 v[2:17], v[54:57], v[114:117], v[2:17]
	s_waitcnt lgkmcnt(3)
	v_mfma_f32_32x32x16_bf16 v[18:33], v[54:57], v[118:121], v[18:33]
	s_waitcnt vmcnt(5)
	v_mfma_f32_32x32x16_bf16 v[2:17], v[62:65], v[106:109], v[2:17]
	s_waitcnt lgkmcnt(2)
	v_mfma_f32_32x32x16_bf16 v[18:33], v[62:65], v[110:113], v[18:33]
	s_waitcnt vmcnt(4)
	v_mfma_f32_32x32x16_bf16 v[2:17], v[70:73], v[98:101], v[2:17]
	s_waitcnt lgkmcnt(1)
	v_mfma_f32_32x32x16_bf16 v[18:33], v[70:73], v[102:105], v[18:33]
	s_nop 9
	v_max_f32_e32 v166, 0, v3
	v_max_f32_e32 v2, 0, v2
	v_max_f32_e32 v167, 0, v18
	v_max_f32_e32 v3, 0, v19
	s_waitcnt lgkmcnt(0)
	v_pk_mul_f32 v[18:19], v[152:153], v[166:167]
	s_nop 0
	v_pk_fma_f32 v[2:3], v[152:153], v[2:3], v[18:19] op_sel:[0,0,1] op_sel_hi:[1,1,0]
	s_nop 0
	v_pk_add_f32 v[78:79], v[78:79], v[2:3]
	v_max_f32_e32 v19, 0, v20
	v_max_f32_e32 v18, 0, v5
	v_max_f32_e32 v2, 0, v4
	v_max_f32_e32 v3, 0, v21
	v_pk_mul_f32 v[4:5], v[152:153], v[18:19]
	s_nop 0
	v_pk_fma_f32 v[2:3], v[152:153], v[2:3], v[4:5] op_sel:[0,0,1] op_sel_hi:[1,1,0]
	s_nop 0
	v_pk_add_f32 v[80:81], v[80:81], v[2:3]
	v_max_f32_e32 v5, 0, v22
	v_max_f32_e32 v4, 0, v7
	v_max_f32_e32 v2, 0, v6
	v_max_f32_e32 v3, 0, v23
	v_pk_mul_f32 v[4:5], v[152:153], v[4:5]
	s_nop 0
	v_pk_fma_f32 v[2:3], v[152:153], v[2:3], v[4:5] op_sel:[0,0,1] op_sel_hi:[1,1,0]
	s_nop 0
	v_pk_add_f32 v[74:75], v[74:75], v[2:3]
	v_max_f32_e32 v5, 0, v24
	v_max_f32_e32 v4, 0, v9
	v_max_f32_e32 v2, 0, v8
	v_max_f32_e32 v3, 0, v25
	v_pk_mul_f32 v[4:5], v[152:153], v[4:5]
	s_nop 0
	v_pk_fma_f32 v[2:3], v[152:153], v[2:3], v[4:5] op_sel:[0,0,1] op_sel_hi:[1,1,0]
	s_nop 0
	v_pk_add_f32 v[76:77], v[76:77], v[2:3]
	v_max_f32_e32 v5, 0, v26
	v_max_f32_e32 v4, 0, v11
	v_max_f32_e32 v2, 0, v10
	v_max_f32_e32 v3, 0, v27
	v_pk_mul_f32 v[4:5], v[152:153], v[4:5]
	s_nop 0
	v_pk_fma_f32 v[2:3], v[152:153], v[2:3], v[4:5] op_sel:[0,0,1] op_sel_hi:[1,1,0]
	s_nop 0
	v_pk_add_f32 v[66:67], v[66:67], v[2:3]
	v_max_f32_e32 v5, 0, v28
	v_max_f32_e32 v4, 0, v13
	v_max_f32_e32 v2, 0, v12
	v_max_f32_e32 v3, 0, v29
	v_pk_mul_f32 v[4:5], v[152:153], v[4:5]
	s_nop 0
	v_pk_fma_f32 v[2:3], v[152:153], v[2:3], v[4:5] op_sel:[0,0,1] op_sel_hi:[1,1,0]
	s_nop 0
	v_pk_add_f32 v[68:69], v[68:69], v[2:3]
	v_max_f32_e32 v5, 0, v30
	v_max_f32_e32 v4, 0, v15
	v_max_f32_e32 v2, 0, v14
	v_max_f32_e32 v3, 0, v31
	v_pk_mul_f32 v[4:5], v[152:153], v[4:5]
	s_nop 0
	v_pk_fma_f32 v[2:3], v[152:153], v[2:3], v[4:5] op_sel:[0,0,1] op_sel_hi:[1,1,0]
	s_nop 0
	v_pk_add_f32 v[58:59], v[58:59], v[2:3]
	v_max_f32_e32 v5, 0, v32
	v_max_f32_e32 v4, 0, v17
	v_max_f32_e32 v2, 0, v16
	v_max_f32_e32 v3, 0, v33
	v_pk_mul_f32 v[4:5], v[152:153], v[4:5]
	s_waitcnt vmcnt(3)
	v_mfma_f32_32x32x16_bf16 v[18:33], v[82:85], v[122:125], 0
	v_fma_f32 v2, v152, v2, v5
	v_fma_f32 v3, v153, v3, v4
	v_add_f32_e64 v60, v60, v2
	v_add_f32_e64 v61, v61, v3
	v_mfma_f32_32x32x16_bf16 v[2:17], v[82:85], v[126:129], 0
	s_waitcnt vmcnt(2)
	v_mfma_f32_32x32x16_bf16 v[2:17], v[86:89], v[118:121], v[2:17]
	v_mfma_f32_32x32x16_bf16 v[18:33], v[86:89], v[114:117], v[18:33]
	s_waitcnt vmcnt(1)
	v_mfma_f32_32x32x16_bf16 v[2:17], v[90:93], v[110:113], v[2:17]
	v_mfma_f32_32x32x16_bf16 v[18:33], v[90:93], v[106:109], v[18:33]
	s_waitcnt vmcnt(0)
	v_mfma_f32_32x32x16_bf16 v[2:17], v[94:97], v[102:105], v[2:17]
	v_mfma_f32_32x32x16_bf16 v[18:33], v[94:97], v[98:101], v[18:33]
	s_nop 10
	v_max_f32_e32 v99, 0, v2
	v_max_f32_e32 v98, 0, v19
	v_max_f32_e32 v18, 0, v18
	v_max_f32_e32 v19, 0, v3
	v_pk_mul_f32 v[2:3], v[152:153], v[98:99]
	s_nop 0
	v_pk_fma_f32 v[2:3], v[152:153], v[18:19], v[2:3] op_sel:[0,0,1] op_sel_hi:[1,1,0]
	s_nop 0
	v_pk_add_f32 v[46:47], v[46:47], v[2:3]
	v_max_f32_e32 v19, 0, v4
	v_max_f32_e32 v18, 0, v21
	v_max_f32_e32 v2, 0, v20
	v_max_f32_e32 v3, 0, v5
	v_pk_mul_f32 v[4:5], v[152:153], v[18:19]
	s_nop 0
	v_pk_fma_f32 v[2:3], v[152:153], v[2:3], v[4:5] op_sel:[0,0,1] op_sel_hi:[1,1,0]
	s_nop 0
	v_pk_add_f32 v[48:49], v[48:49], v[2:3]
	v_max_f32_e32 v5, 0, v6
	v_max_f32_e32 v4, 0, v23
	v_max_f32_e32 v2, 0, v22
	v_max_f32_e32 v3, 0, v7
	v_pk_mul_f32 v[4:5], v[152:153], v[4:5]
	s_nop 0
	v_pk_fma_f32 v[2:3], v[152:153], v[2:3], v[4:5] op_sel:[0,0,1] op_sel_hi:[1,1,0]
	s_nop 0
	v_pk_add_f32 v[42:43], v[42:43], v[2:3]
	v_max_f32_e32 v5, 0, v8
	v_max_f32_e32 v4, 0, v25
	v_max_f32_e32 v2, 0, v24
	v_max_f32_e32 v3, 0, v9
	v_pk_mul_f32 v[4:5], v[152:153], v[4:5]
	s_nop 0
	v_pk_fma_f32 v[2:3], v[152:153], v[2:3], v[4:5] op_sel:[0,0,1] op_sel_hi:[1,1,0]
	s_nop 0
	v_pk_add_f32 v[44:45], v[44:45], v[2:3]
	v_max_f32_e32 v5, 0, v10
	v_max_f32_e32 v4, 0, v27
	v_max_f32_e32 v2, 0, v26
	v_max_f32_e32 v3, 0, v11
	v_pk_mul_f32 v[4:5], v[152:153], v[4:5]
	s_nop 0
	v_pk_fma_f32 v[2:3], v[152:153], v[2:3], v[4:5] op_sel:[0,0,1] op_sel_hi:[1,1,0]
	s_nop 0
	v_pk_add_f32 v[38:39], v[38:39], v[2:3]
	v_max_f32_e32 v5, 0, v12
	v_max_f32_e32 v4, 0, v29
	v_max_f32_e32 v2, 0, v28
	v_max_f32_e32 v3, 0, v13
	v_pk_mul_f32 v[4:5], v[152:153], v[4:5]
	s_nop 0
	v_pk_fma_f32 v[2:3], v[152:153], v[2:3], v[4:5] op_sel:[0,0,1] op_sel_hi:[1,1,0]
	s_nop 0
	v_pk_add_f32 v[40:41], v[40:41], v[2:3]
	v_max_f32_e32 v5, 0, v14
	v_max_f32_e32 v4, 0, v31
	v_max_f32_e32 v2, 0, v30
	v_max_f32_e32 v3, 0, v15
	v_pk_mul_f32 v[4:5], v[152:153], v[4:5]
	s_nop 0
	v_pk_fma_f32 v[2:3], v[152:153], v[2:3], v[4:5] op_sel:[0,0,1] op_sel_hi:[1,1,0]
	s_nop 0
	v_pk_add_f32 v[34:35], v[34:35], v[2:3]
	v_max_f32_e32 v5, 0, v16
	v_max_f32_e32 v4, 0, v33
	v_max_f32_e32 v2, 0, v32
	v_max_f32_e32 v3, 0, v17
	v_pk_mul_f32 v[4:5], v[152:153], v[4:5]
	s_nop 0
	v_pk_fma_f32 v[2:3], v[152:153], v[2:3], v[4:5] op_sel:[0,0,1] op_sel_hi:[1,1,0]
	s_nop 0
	v_pk_add_f32 v[36:37], v[36:37], v[2:3]
	s_cbranch_scc0 .LBB0_1414
	v_cmp_ge_i32_e32 vcc, s6, v162
	s_and_saveexec_b64 s[4:5], vcc
	s_cbranch_execz .LBB0_1417
	v_lshlrev_b32_e32 v2, 6, v161
	v_ashrrev_i32_e32 v3, 31, v2
	v_lshl_add_u64 v[2:3], v[2:3], 2, v[150:151]
	global_store_dwordx4 v[2:3], v[78:81], off
	global_store_dwordx4 v[2:3], v[74:77], off offset:32
	global_store_dwordx4 v[2:3], v[66:69], off offset:64
	global_store_dwordx4 v[2:3], v[58:61], off offset:96

.LBB0_1544:
	s_bitcmp1_b32 s5, 0
	s_cselect_b32 s25, 0x13000, 0
	s_add_i32 s25, s25, 0
	v_add_u32_e32 v130, s25, v146
	v_add_u32_e32 v131, v130, v126
	v_add3_u32 v110, s25, v125, v124
	v_add_u32_e32 v144, 0x1000, v131
	v_add_u32_e32 v145, 0x2000, v131
	v_add_u32_e32 v180, 0x3000, v131
	ds_read_b64 v[98:99], v110 offset:61440
	ds_read_b64 v[100:101], v110 offset:61952
	ds_read_b64 v[102:103], v110 offset:62464
	ds_read_b64 v[104:105], v110 offset:62976
	ds_read_b64 v[106:107], v110 offset:63488
	ds_read_b64 v[108:109], v110 offset:64000
	ds_read_b64 v[112:113], v110 offset:65024
	ds_read_b64 v[110:111], v110 offset:64512
	ds_read_b64 v[114:115], v131
	ds_read_b64 v[116:117], v131 offset:32
	ds_read_b64 v[132:133], v131 offset:64
	ds_read_b64 v[134:135], v131 offset:96
	ds_read_b64 v[136:137], v144 offset:256
	ds_read_b64 v[138:139], v144 offset:288
	ds_read_b64 v[140:141], v144 offset:320
	ds_read_b64 v[142:143], v144 offset:352
	ds_read_b64 v[148:149], v145 offset:512
	ds_read_b64 v[150:151], v145 offset:544
	ds_read_b64 v[152:153], v145 offset:576
	ds_read_b64 v[154:155], v145 offset:608
	ds_read_b64 v[156:157], v180 offset:768
	ds_read_b64 v[158:159], v180 offset:800
	ds_read_b64 v[160:161], v180 offset:832
	ds_read_b64 v[162:163], v180 offset:864
	v_readlane_b32 s4, v123, s5
	v_cvt_pk_bf16_f32 v78, v62, v63
	v_cvt_pk_bf16_f32 v79, v64, v65
	v_cvt_pk_bf16_f32 v80, v54, v55
	v_cvt_pk_bf16_f32 v81, v56, v57
	v_cvt_pk_bf16_f32 v86, v58, v59
	v_cvt_pk_bf16_f32 v87, v60, v61
	v_cvt_pk_bf16_f32 v88, v46, v47
	v_cvt_pk_bf16_f32 v89, v48, v49
	v_cvt_pk_bf16_f32 v90, v50, v51
	v_cvt_pk_bf16_f32 v91, v52, v53
	v_cvt_pk_bf16_f32 v92, v42, v43
	v_cvt_pk_bf16_f32 v93, v44, v45
	v_cvt_pk_bf16_f32 v94, v38, v39
	v_cvt_pk_bf16_f32 v95, v40, v41
	v_cvt_pk_bf16_f32 v96, v34, v35
	v_cvt_pk_bf16_f32 v97, v36, v37
	v_cvt_pk_bf16_f32 v66, v30, v31
	v_cvt_pk_bf16_f32 v67, v32, v33
	v_cvt_pk_bf16_f32 v68, v26, v27
	v_cvt_pk_bf16_f32 v69, v28, v29
	v_cvt_pk_bf16_f32 v74, v22, v23
	v_cvt_pk_bf16_f32 v75, v24, v25
	v_cvt_pk_bf16_f32 v76, v14, v15
	v_cvt_pk_bf16_f32 v77, v16, v17
	v_cvt_pk_bf16_f32 v70, v18, v19
	v_cvt_pk_bf16_f32 v71, v20, v21
	v_cvt_pk_bf16_f32 v72, v10, v11
	v_cvt_pk_bf16_f32 v73, v12, v13
	v_cvt_pk_bf16_f32 v82, v6, v7
	v_cvt_pk_bf16_f32 v83, v8, v9
	v_cvt_pk_bf16_f32 v84, v2, v3
	v_cvt_pk_bf16_f32 v85, v4, v5
	s_waitcnt lgkmcnt(15)
	v_lshlrev_b32_e32 v164, 16, v98
	v_and_b32_e32 v165, 0xffff0000, v98
	v_lshlrev_b32_e32 v166, 16, v99
	v_and_b32_e32 v167, 0xffff0000, v99
	s_waitcnt lgkmcnt(15)
	v_lshlrev_b32_e32 v168, 16, v106
	v_and_b32_e32 v169, 0xffff0000, v106
	v_lshlrev_b32_e32 v170, 16, v107
	v_and_b32_e32 v171, 0xffff0000, v107
	v_lshlrev_b32_e32 v98, 16, v100
	v_and_b32_e32 v99, 0xffff0000, v100
	v_lshlrev_b32_e32 v100, 16, v101
	v_and_b32_e32 v101, 0xffff0000, v101
	v_lshlrev_b32_e32 v106, 16, v108
	v_and_b32_e32 v107, 0xffff0000, v108
	v_lshlrev_b32_e32 v108, 16, v109
	v_and_b32_e32 v109, 0xffff0000, v109
	v_lshlrev_b32_e32 v172, 16, v102
	v_and_b32_e32 v173, 0xffff0000, v102
	v_lshlrev_b32_e32 v174, 16, v103
	v_and_b32_e32 v175, 0xffff0000, v103
	s_waitcnt lgkmcnt(15)
	v_lshlrev_b32_e32 v176, 16, v110
	v_and_b32_e32 v177, 0xffff0000, v110
	v_lshlrev_b32_e32 v178, 16, v111
	v_and_b32_e32 v179, 0xffff0000, v111
	v_lshlrev_b32_e32 v102, 16, v104
	v_and_b32_e32 v103, 0xffff0000, v104
	v_lshlrev_b32_e32 v104, 16, v105
	v_and_b32_e32 v105, 0xffff0000, v105
	v_lshlrev_b32_e32 v110, 16, v112
	v_and_b32_e32 v111, 0xffff0000, v112
	v_lshlrev_b32_e32 v112, 16, v113
	v_and_b32_e32 v113, 0xffff0000, v113
	s_waitcnt lgkmcnt(14)
	v_mfma_f32_16x16x32_bf16 v[164:167], v[114:117], v[78:81], v[164:167]
	v_mfma_f32_16x16x32_bf16 v[114:117], v[114:117], v[86:89], v[168:171]
	s_waitcnt lgkmcnt(10)
	v_mfma_f32_16x16x32_bf16 v[98:101], v[136:139], v[78:81], v[98:101]
	v_mfma_f32_16x16x32_bf16 v[106:109], v[136:139], v[86:89], v[106:109]
	s_waitcnt lgkmcnt(6)
	v_mfma_f32_16x16x32_bf16 v[136:139], v[148:151], v[78:81], v[172:175]
	v_mfma_f32_16x16x32_bf16 v[148:151], v[148:151], v[86:89], v[176:179]
	s_waitcnt lgkmcnt(2)
	v_mfma_f32_16x16x32_bf16 v[102:105], v[156:159], v[78:81], v[102:105]
	v_mfma_f32_16x16x32_bf16 v[110:113], v[156:159], v[86:89], v[110:113]
	v_mfma_f32_16x16x32_bf16 v[156:159], v[132:135], v[90:93], v[164:167]
	v_mfma_f32_16x16x32_bf16 v[114:117], v[132:135], v[94:97], v[114:117]
	v_mfma_f32_16x16x32_bf16 v[98:101], v[140:143], v[90:93], v[98:101]
	v_mfma_f32_16x16x32_bf16 v[106:109], v[140:143], v[94:97], v[106:109]
	v_mfma_f32_16x16x32_bf16 v[132:135], v[152:155], v[90:93], v[136:139]
	s_nop 2
	ds_read_b64 v[136:137], v131 offset:128
	ds_read_b64 v[138:139], v131 offset:160
	ds_read_b64 v[140:141], v131 offset:192
	ds_read_b64 v[142:143], v131 offset:224
	v_mfma_f32_16x16x32_bf16 v[148:151], v[152:155], v[94:97], v[148:151]
	ds_read_b64 v[152:153], v144 offset:384
	ds_read_b64 v[154:155], v144 offset:416
	ds_read_b64 v[164:165], v144 offset:448
	ds_read_b64 v[166:167], v144 offset:480
	ds_read_b64 v[168:169], v145 offset:640
	ds_read_b64 v[170:171], v145 offset:672
	ds_read_b64 v[172:173], v145 offset:704
	ds_read_b64 v[174:175], v145 offset:736
	ds_read_b64 v[176:177], v180 offset:896
	ds_read_b64 v[178:179], v180 offset:928
	ds_read_b64 v[182:183], v180 offset:992
	ds_read_b64 v[180:181], v180 offset:960
	s_waitcnt lgkmcnt(15)
	v_mfma_f32_16x16x32_bf16 v[102:105], v[160:163], v[90:93], v[102:105]
	v_mfma_f32_16x16x32_bf16 v[110:113], v[160:163], v[94:97], v[110:113]
	s_add_i32 s25, s25, 0x8800
	s_waitcnt lgkmcnt(14)
	v_mfma_f32_16x16x32_bf16 v[156:159], v[136:139], v[66:69], v[156:159]
	v_add_u32_e32 v144, s25, v129
	v_mfma_f32_16x16x32_bf16 v[114:117], v[136:139], v[74:77], v[114:117]
	ds_read_b64_tr_b16 v[136:137], v144
	ds_read_b64_tr_b16 v[138:139], v144 offset:4352
	s_waitcnt lgkmcnt(8)
	v_mfma_f32_16x16x32_bf16 v[98:101], v[152:155], v[66:69], v[98:101]
	v_mfma_f32_16x16x32_bf16 v[106:109], v[152:155], v[74:77], v[106:109]
	ds_read_b64_tr_b16 v[152:153], v144 offset:8704
	ds_read_b64_tr_b16 v[154:155], v144 offset:13056
	ds_read_b64_tr_b16 v[160:161], v144 offset:32
	s_waitcnt lgkmcnt(3)
	v_mfma_f32_16x16x32_bf16 v[132:135], v[168:171], v[66:69], v[132:135]
	v_mfma_f32_16x16x32_bf16 v[148:151], v[168:171], v[74:77], v[148:151]
	ds_read_b64_tr_b16 v[162:163], v144 offset:4384
	ds_read_b64_tr_b16 v[168:169], v144 offset:8736
	ds_read_b64_tr_b16 v[170:171], v144 offset:13088
	v_mfma_f32_16x16x32_bf16 v[156:159], v[140:143], v[70:73], v[156:159]
	v_mfma_f32_16x16x32_bf16 v[114:117], v[140:143], v[82:85], v[114:117]
	ds_read_b64_tr_b16 v[140:141], v144 offset:64
	ds_read_b64_tr_b16 v[142:143], v144 offset:4416
	s_waitcnt lgkmcnt(1)
	v_mfma_f32_16x16x32_bf16 v[102:105], v[176:179], v[66:69], v[102:105]
	v_mfma_f32_16x16x32_bf16 v[110:113], v[176:179], v[74:77], v[110:113]
	v_mfma_f32_16x16x32_bf16 v[176:179], v[164:167], v[70:73], v[98:101]
	s_nop 2
	ds_read_b64_tr_b16 v[184:185], v144 offset:8768
	ds_read_b64_tr_b16 v[186:187], v144 offset:13120
	v_mfma_f32_16x16x32_bf16 v[106:109], v[164:167], v[82:85], v[106:109]
	ds_read_b64_tr_b16 v[164:165], v144 offset:96
	ds_read_b64_tr_b16 v[166:167], v144 offset:4448
	v_mfma_f32_16x16x32_bf16 v[132:135], v[172:175], v[70:73], v[132:135]
	v_mfma_f32_16x16x32_bf16 v[148:151], v[172:175], v[82:85], v[148:151]
	ds_read_b64_tr_b16 v[172:173], v144 offset:8800
	ds_read_b64_tr_b16 v[174:175], v144 offset:13152
	s_waitcnt lgkmcnt(0)
	v_mfma_f32_16x16x32_bf16 v[188:191], v[180:183], v[70:73], v[102:105]
	s_waitcnt lgkmcnt(0)
	v_mfma_f32_16x16x32_bf16 v[180:183], v[180:183], v[82:85], v[110:113]
	v_cvt_pk_bf16_f32 v98, v156, v157
	v_cvt_pk_bf16_f32 v99, v158, v159
	v_cvt_pk_bf16_f32 v100, v176, v177
	v_cvt_pk_bf16_f32 v101, v178, v179
	v_cvt_pk_bf16_f32 v102, v114, v115
	v_cvt_pk_bf16_f32 v103, v116, v117
	v_cvt_pk_bf16_f32 v104, v106, v107
	v_cvt_pk_bf16_f32 v105, v108, v109
	v_pk_mul_f32 v[64:65], v[64:65], s[4:5] op_sel_hi:[1,0]
	v_pk_mul_f32 v[62:63], v[62:63], s[4:5] op_sel_hi:[1,0]
	v_pk_mul_f32 v[60:61], v[60:61], s[4:5] op_sel_hi:[1,0]
	v_pk_mul_f32 v[58:59], v[58:59], s[4:5] op_sel_hi:[1,0]
	v_mfma_f32_16x16x32_bf16 v[62:65], v[136:139], v[98:101], v[62:65]
	v_mul_f32_e64 v56, v56, s4
	v_mul_f32_e64 v57, v57, s4
	v_pk_mul_f32 v[54:55], v[54:55], s[4:5] op_sel_hi:[1,0]
	v_pk_mul_f32 v[48:49], v[48:49], s[4:5] op_sel_hi:[1,0]
	v_mfma_f32_16x16x32_bf16 v[58:61], v[136:139], v[102:105], v[58:61]
	v_mul_f32_e64 v46, v46, s4
	v_mul_f32_e64 v47, v47, s4
	v_pk_mul_f32 v[52:53], v[52:53], s[4:5] op_sel_hi:[1,0]
	v_pk_mul_f32 v[50:51], v[50:51], s[4:5] op_sel_hi:[1,0]
	v_pk_mul_f32 v[40:41], v[40:41], s[4:5] op_sel_hi:[1,0]
	v_pk_mul_f32 v[38:39], v[38:39], s[4:5] op_sel_hi:[1,0]
	v_pk_mul_f32 v[44:45], v[44:45], s[4:5] op_sel_hi:[1,0]
	v_pk_mul_f32 v[42:43], v[42:43], s[4:5] op_sel_hi:[1,0]
	v_pk_mul_f32 v[36:37], v[36:37], s[4:5] op_sel_hi:[1,0]
	v_pk_mul_f32 v[34:35], v[34:35], s[4:5] op_sel_hi:[1,0]
	v_mfma_f32_16x16x32_bf16 v[54:57], v[160:163], v[98:101], v[54:57]
	v_cvt_pk_bf16_f32 v106, v132, v133
	v_cvt_pk_bf16_f32 v107, v134, v135
	v_cvt_pk_bf16_f32 v108, v188, v189
	v_mfma_f32_16x16x32_bf16 v[46:49], v[160:163], v[102:105], v[46:49]
	v_cvt_pk_bf16_f32 v109, v190, v191
	v_cvt_pk_bf16_f32 v110, v148, v149
	v_cvt_pk_bf16_f32 v111, v150, v151
	v_mfma_f32_16x16x32_bf16 v[50:53], v[140:143], v[98:101], v[50:53]
	v_cvt_pk_bf16_f32 v112, v180, v181
	v_cvt_pk_bf16_f32 v113, v182, v183
	v_add_u32_e32 v145, 0x4000, v131
	v_mfma_f32_16x16x32_bf16 v[38:41], v[140:143], v[102:105], v[38:41]
	v_add_u32_e32 v196, 0x5000, v131
	v_add_u32_e32 v197, 0x6000, v131
	v_add_u32_e32 v131, 0x7000, v131
	v_mfma_f32_16x16x32_bf16 v[42:45], v[164:167], v[98:101], v[42:45]
	ds_read_b64 v[132:133], v145 offset:1024
	ds_read_b64 v[134:135], v145 offset:1056
	ds_read_b64 v[114:115], v145 offset:1088
	ds_read_b64 v[116:117], v145 offset:1120
	ds_read_b64 v[136:137], v196 offset:1280
	ds_read_b64 v[138:139], v196 offset:1312
	ds_read_b64 v[140:141], v196 offset:1344
	ds_read_b64 v[142:143], v196 offset:1376
	v_mfma_f32_16x16x32_bf16 v[34:37], v[164:167], v[102:105], v[34:37]
	v_mfma_f32_16x16x32_bf16 v[62:65], v[152:155], v[106:109], v[62:65]
	v_mfma_f32_16x16x32_bf16 v[58:61], v[152:155], v[110:113], v[58:61]
	ds_read_b64 v[148:149], v197 offset:1536
	ds_read_b64 v[150:151], v197 offset:1568
	ds_read_b64 v[152:153], v197 offset:1600
	ds_read_b64 v[154:155], v197 offset:1632
	ds_read_b64 v[156:157], v131 offset:1792
	ds_read_b64 v[158:159], v131 offset:1824
	ds_read_b64 v[160:161], v131 offset:1856
	ds_read_b64 v[162:163], v131 offset:1888
	v_mfma_f32_16x16x32_bf16 v[54:57], v[168:171], v[106:109], v[54:57]
	v_mfma_f32_16x16x32_bf16 v[46:49], v[168:171], v[110:113], v[46:49]
	v_mfma_f32_16x16x32_bf16 v[50:53], v[184:187], v[106:109], v[50:53]
	v_mfma_f32_16x16x32_bf16 v[38:41], v[184:187], v[110:113], v[38:41]
	v_mfma_f32_16x16x32_bf16 v[42:45], v[172:175], v[106:109], v[42:45]
	v_mfma_f32_16x16x32_bf16 v[34:37], v[172:175], v[110:113], v[34:37]
	ds_read_b64_tr_b16 v[164:165], v144 offset:128
	ds_read_b64_tr_b16 v[166:167], v144 offset:4480
	ds_read_b64_tr_b16 v[168:169], v144 offset:8832
	ds_read_b64_tr_b16 v[170:171], v144 offset:13184
	ds_read_b64_tr_b16 v[172:173], v144 offset:160
	ds_read_b64_tr_b16 v[174:175], v144 offset:4512
	ds_read_b64_tr_b16 v[176:177], v144 offset:8864
	ds_read_b64_tr_b16 v[178:179], v144 offset:13216
	ds_read_b64_tr_b16 v[180:181], v144 offset:192
	ds_read_b64_tr_b16 v[182:183], v144 offset:4544
	ds_read_b64_tr_b16 v[184:185], v144 offset:8896
	ds_read_b64_tr_b16 v[186:187], v144 offset:13248
	ds_read_b64_tr_b16 v[188:189], v144 offset:224
	ds_read_b64_tr_b16 v[190:191], v144 offset:4576
	ds_read_b64_tr_b16 v[192:193], v144 offset:8928
	ds_read_b64_tr_b16 v[194:195], v144 offset:13280
	s_nop 0
	s_waitcnt lgkmcnt(0)
	v_pk_mul_f32 v[32:33], v[32:33], s[4:5] op_sel_hi:[1,0]
	v_pk_mul_f32 v[30:31], v[30:31], s[4:5] op_sel_hi:[1,0]
	v_pk_mul_f32 v[24:25], v[24:25], s[4:5] op_sel_hi:[1,0]
	v_pk_mul_f32 v[22:23], v[22:23], s[4:5] op_sel_hi:[1,0]
	v_mfma_f32_16x16x32_bf16 v[30:33], v[164:167], v[98:101], v[30:33]
	v_mul_f32_e64 v28, v28, s4
	v_mul_f32_e64 v29, v29, s4
	v_pk_mul_f32 v[26:27], v[26:27], s[4:5] op_sel_hi:[1,0]
	v_pk_mul_f32 v[16:17], v[16:17], s[4:5] op_sel_hi:[1,0]
	v_mfma_f32_16x16x32_bf16 v[22:25], v[164:167], v[102:105], v[22:25]
	v_mul_f32_e64 v14, v14, s4
	v_mul_f32_e64 v15, v15, s4
	v_pk_mul_f32 v[20:21], v[20:21], s[4:5] op_sel_hi:[1,0]
	v_pk_mul_f32 v[18:19], v[18:19], s[4:5] op_sel_hi:[1,0]
	v_pk_mul_f32 v[8:9], v[8:9], s[4:5] op_sel_hi:[1,0]
	v_pk_mul_f32 v[6:7], v[6:7], s[4:5] op_sel_hi:[1,0]
	v_mfma_f32_16x16x32_bf16 v[30:33], v[168:171], v[106:109], v[30:33]
	v_mul_f32_e64 v12, v12, s4
	v_mul_f32_e64 v13, v13, s4
	v_pk_mul_f32 v[10:11], v[10:11], s[4:5] op_sel_hi:[1,0]
	v_pk_mul_f32 v[4:5], v[4:5], s[4:5] op_sel_hi:[1,0]
	v_mfma_f32_16x16x32_bf16 v[22:25], v[168:171], v[110:113], v[22:25]
	v_mul_f32_e64 v2, v2, s4
	v_mul_f32_e64 v3, v3, s4
	v_mfma_f32_16x16x32_bf16 v[26:29], v[172:175], v[98:101], v[26:29]
	v_mfma_f32_16x16x32_bf16 v[14:17], v[172:175], v[102:105], v[14:17]
	v_mfma_f32_16x16x32_bf16 v[18:21], v[180:183], v[98:101], v[18:21]
	v_mfma_f32_16x16x32_bf16 v[6:9], v[180:183], v[102:105], v[6:9]
	s_waitcnt lgkmcnt(7)
	v_mfma_f32_16x16x32_bf16 v[164:167], v[78:81], v[132:135], 0
	v_mfma_f32_16x16x32_bf16 v[132:135], v[86:89], v[132:135], 0
	s_waitcnt lgkmcnt(5)
	v_mfma_f32_16x16x32_bf16 v[168:171], v[78:81], v[136:139], 0
	v_mfma_f32_16x16x32_bf16 v[136:139], v[86:89], v[136:139], 0
	s_waitcnt lgkmcnt(3)
	v_mfma_f32_16x16x32_bf16 v[172:175], v[78:81], v[148:151], 0
	v_mfma_f32_16x16x32_bf16 v[148:151], v[86:89], v[148:151], 0
	s_waitcnt lgkmcnt(1)
	v_mfma_f32_16x16x32_bf16 v[78:81], v[78:81], v[156:159], 0
	v_mfma_f32_16x16x32_bf16 v[10:13], v[188:191], v[98:101], v[10:13]
	v_mfma_f32_16x16x32_bf16 v[2:5], v[188:191], v[102:105], v[2:5]
	v_mfma_f32_16x16x32_bf16 v[26:29], v[176:179], v[106:109], v[26:29]
	v_mfma_f32_16x16x32_bf16 v[14:17], v[176:179], v[110:113], v[14:17]
	v_mfma_f32_16x16x32_bf16 v[18:21], v[184:187], v[106:109], v[18:21]
	v_mfma_f32_16x16x32_bf16 v[6:9], v[184:187], v[110:113], v[6:9]
	v_mfma_f32_16x16x32_bf16 v[86:89], v[86:89], v[156:159], 0
	v_mfma_f32_16x16x32_bf16 v[156:159], v[90:93], v[114:117], v[164:167]
	v_mfma_f32_16x16x32_bf16 v[114:117], v[94:97], v[114:117], v[132:135]
	v_mfma_f32_16x16x32_bf16 v[132:135], v[90:93], v[140:143], v[168:171]
	s_nop 0
	ds_read_b64 v[164:165], v145 offset:1152
	ds_read_b64 v[166:167], v145 offset:1184
	s_nop 0
	ds_read_b64 v[168:169], v145 offset:1216
	ds_read_b64 v[170:171], v145 offset:1248
	v_mfma_f32_16x16x32_bf16 v[136:139], v[94:97], v[140:143], v[136:139]
	v_mfma_f32_16x16x32_bf16 v[140:143], v[90:93], v[152:155], v[172:175]
	v_mfma_f32_16x16x32_bf16 v[148:151], v[94:97], v[152:155], v[148:151]
	ds_read_b64 v[152:153], v196 offset:1408
	ds_read_b64 v[154:155], v196 offset:1440
	s_nop 0
	ds_read_b64 v[172:173], v196 offset:1472
	ds_read_b64 v[174:175], v196 offset:1504
	ds_read_b64 v[176:177], v197 offset:1664
	ds_read_b64 v[178:179], v197 offset:1696
	s_waitcnt lgkmcnt(10)
	v_mfma_f32_16x16x32_bf16 v[78:81], v[90:93], v[160:163], v[78:81]
	ds_read_b64 v[90:91], v197 offset:1728
	ds_read_b64 v[92:93], v197 offset:1760
	ds_read_b64 v[180:181], v131 offset:1920
	ds_read_b64 v[182:183], v131 offset:1952
	ds_read_b64 v[184:185], v131 offset:1984
	ds_read_b64 v[186:187], v131 offset:2016
	v_mfma_f32_16x16x32_bf16 v[10:13], v[192:195], v[106:109], v[10:13]
	v_mfma_f32_16x16x32_bf16 v[2:5], v[192:195], v[110:113], v[2:5]
	v_mfma_f32_16x16x32_bf16 v[86:89], v[94:97], v[160:163], v[86:89]
	s_waitcnt lgkmcnt(14)
	v_mfma_f32_16x16x32_bf16 v[94:97], v[66:69], v[164:167], v[156:159]
	v_add_u32_e32 v160, v130, v127
	s_waitcnt lgkmcnt(10)
	v_mfma_f32_16x16x32_bf16 v[132:135], v[66:69], v[152:155], v[132:135]
	v_add_u32_e32 v156, 0xd800, v160
	v_mfma_f32_16x16x32_bf16 v[114:117], v[74:77], v[164:167], v[114:117]
	v_mfma_f32_16x16x32_bf16 v[136:139], v[74:77], v[152:155], v[136:139]
	v_add_u32_e32 v152, 0xd000, v160
	s_waitcnt lgkmcnt(6)
	v_mfma_f32_16x16x32_bf16 v[140:143], v[66:69], v[176:179], v[140:143]
	v_mfma_f32_16x16x32_bf16 v[148:151], v[74:77], v[176:179], v[148:151]
	s_waitcnt lgkmcnt(2)
	v_mfma_f32_16x16x32_bf16 v[66:69], v[66:69], v[180:183], v[78:81]
	v_mfma_f32_16x16x32_bf16 v[78:81], v[70:73], v[168:171], v[94:97]
	v_mfma_f32_16x16x32_bf16 v[94:97], v[70:73], v[172:175], v[132:135]
	s_nop 2
	v_add_u32_e32 v134, 0xc800, v160
	v_add_u32_e32 v160, 0xe000, v160
	v_mfma_f32_16x16x32_bf16 v[74:77], v[74:77], v[180:183], v[86:89]
	v_mfma_f32_16x16x32_bf16 v[86:89], v[82:85], v[168:171], v[114:117]
	v_mfma_f32_16x16x32_bf16 v[114:117], v[82:85], v[172:175], v[136:139]
	ds_read_b64 v[130:131], v134 offset:1024
	ds_read_b64 v[132:133], v134 offset:1056
	s_nop 1
	ds_read_b64 v[136:137], v134 offset:1120
	ds_read_b64 v[134:135], v134 offset:1088
	v_mfma_f32_16x16x32_bf16 v[138:141], v[70:73], v[90:93], v[140:143]
	s_nop 2
	ds_read_b64 v[142:143], v152 offset:1280
	ds_read_b64 v[144:145], v152 offset:1312
	ds_read_b64 v[154:155], v152 offset:1376
	ds_read_b64 v[152:153], v152 offset:1344
	v_mfma_f32_16x16x32_bf16 v[90:93], v[82:85], v[90:93], v[148:151]
	s_nop 2
	ds_read_b64 v[148:149], v156 offset:1536
	ds_read_b64 v[150:151], v156 offset:1568
	ds_read_b64 v[158:159], v156 offset:1632
	ds_read_b64 v[156:157], v156 offset:1600
	s_waitcnt lgkmcnt(12)
	v_mfma_f32_16x16x32_bf16 v[66:69], v[70:73], v[184:187], v[66:69]
	ds_read_b64 v[70:71], v160 offset:1792
	ds_read_b64 v[72:73], v160 offset:1824
	ds_read_b64 v[162:163], v160 offset:1888
	ds_read_b64 v[160:161], v160 offset:1856
	v_mfma_f32_16x16x32_bf16 v[74:77], v[82:85], v[184:187], v[74:77]
	s_waitcnt lgkmcnt(14)
	v_mfma_f32_16x16x32_bf16 v[78:81], v[98:101], v[130:133], v[78:81]
	v_mfma_f32_16x16x32_bf16 v[82:85], v[102:105], v[130:133], v[86:89]
	s_waitcnt lgkmcnt(10)
	v_mfma_f32_16x16x32_bf16 v[86:89], v[98:101], v[142:145], v[94:97]
	v_mfma_f32_16x16x32_bf16 v[94:97], v[102:105], v[142:145], v[114:117]
	s_waitcnt lgkmcnt(6)
	v_mfma_f32_16x16x32_bf16 v[114:117], v[98:101], v[148:151], v[138:141]
	v_mfma_f32_16x16x32_bf16 v[90:93], v[102:105], v[148:151], v[90:93]
	s_waitcnt lgkmcnt(2)
	v_mfma_f32_16x16x32_bf16 v[66:69], v[98:101], v[70:73], v[66:69]
	v_mfma_f32_16x16x32_bf16 v[70:73], v[102:105], v[70:73], v[74:77]
	v_mfma_f32_16x16x32_bf16 v[74:77], v[106:109], v[134:137], v[78:81]
	v_mfma_f32_16x16x32_bf16 v[78:81], v[110:113], v[134:137], v[82:85]
	v_mfma_f32_16x16x32_bf16 v[82:85], v[106:109], v[152:155], v[86:89]
	v_mfma_f32_16x16x32_bf16 v[86:89], v[110:113], v[152:155], v[94:97]
	v_mfma_f32_16x16x32_bf16 v[94:97], v[106:109], v[156:159], v[114:117]
	v_mfma_f32_16x16x32_bf16 v[90:93], v[110:113], v[156:159], v[90:93]
	s_waitcnt lgkmcnt(0)
	v_mfma_f32_16x16x32_bf16 v[66:69], v[106:109], v[160:163], v[66:69]
	v_mfma_f32_16x16x32_bf16 v[70:73], v[110:113], v[160:163], v[70:73]
	v_add_u32_e32 v98, s1, v128
	s_nop 5
	v_cvt_pk_bf16_f32 v66, v66, v67
	v_cvt_pk_bf16_f32 v67, v68, v69
	v_cvt_pk_bf16_f32 v68, v70, v71
	v_add_u32_e32 v70, 16, v98
	v_cvt_pk_bf16_f32 v74, v74, v75
	v_cvt_pk_bf16_f32 v75, v76, v77
	v_cvt_pk_bf16_f32 v77, v80, v81
	v_cvt_pk_bf16_f32 v80, v86, v87
	v_cvt_pk_bf16_f32 v69, v72, v73
	v_ashrrev_i32_e32 v99, 31, v98
	v_add_u32_e32 v72, 32, v98
	v_add_u32_e32 v86, 48, v98
	v_ashrrev_i32_e32 v71, 31, v70
	v_cvt_pk_bf16_f32 v81, v88, v89
	v_lshlrev_b64 v[88:89], 12, v[98:99]
	v_ashrrev_i32_e32 v73, 31, v72
	v_ashrrev_i32_e32 v87, 31, v86
	v_lshlrev_b64 v[70:71], 12, v[70:71]
	v_cvt_pk_bf16_f32 v76, v78, v79
	v_cvt_pk_bf16_f32 v78, v82, v83
	v_cvt_pk_bf16_f32 v79, v84, v85
	v_lshl_add_u64 v[88:89], v[120:121], 0, v[88:89]
	v_lshlrev_b64 v[72:73], 12, v[72:73]
	v_lshlrev_b64 v[86:87], 12, v[86:87]
	v_lshl_add_u64 v[70:71], v[120:121], 0, v[70:71]
	v_cvt_pk_bf16_f32 v82, v94, v95
	v_cvt_pk_bf16_f32 v83, v96, v97
	v_cvt_pk_bf16_f32 v84, v90, v91
	v_cvt_pk_bf16_f32 v85, v92, v93
	global_store_dwordx2 v[88:89], v[74:75], off
	global_store_dwordx2 v[88:89], v[76:77], off offset:32
	v_lshl_add_u64 v[72:73], v[120:121], 0, v[72:73]
	v_lshl_add_u64 v[74:75], v[120:121], 0, v[86:87]
	global_store_dwordx2 v[70:71], v[78:79], off
	global_store_dwordx2 v[70:71], v[80:81], off offset:32
	global_store_dwordx2 v[72:73], v[82:83], off
	global_store_dwordx2 v[72:73], v[84:85], off offset:32
	global_store_dwordx2 v[74:75], v[66:67], off
	global_store_dwordx2 v[74:75], v[68:69], off offset:32
	s_waitcnt lgkmcnt(0)
	s_barrier
	s_add_i32 s5, s5, 1
	s_add_i32 s1, s1, 64
	s_cmpk_eq_i32 s1, 0x800
	s_cbranch_scc0 .LBB0_1544
	s_ashr_i32 s1, s0, 31
	s_lshl_b64 s[4:5], s[0:1], 16
	s_add_u32 s4, s8, s4
	s_addc_u32 s5, s9, s5
	v_lshl_add_u64 v[66:67], v[118:119], 2, s[4:5]
	v_lshlrev_b32_e32 v146, 2, v122
	v_lshl_add_u64 v[66:67], v[66:67], 0, v[146:147]
	v_lshlrev_b32_e32 v146, 11, v1
	v_lshl_add_u64 v[68:69], v[66:67], 0, v[146:147]
	global_store_dword v[68:69], v62, off
	global_store_dword v[68:69], v63, off offset:512
	global_store_dword v[68:69], v64, off offset:1024
	global_store_dword v[68:69], v65, off offset:1536
	global_store_dword v[68:69], v58, off offset:64
	global_store_dword v[68:69], v59, off offset:576
	global_store_dword v[68:69], v60, off offset:1088
	global_store_dword v[68:69], v61, off offset:1600
	v_or_b32_e32 v58, 0x2000, v146
	v_mov_b32_e32 v59, v147
	v_lshl_add_u64 v[60:61], v[66:67], 0, v[58:59]
	global_store_dword v[60:61], v54, off
	v_or_b32_e32 v60, 0x2200, v146
	v_mov_b32_e32 v61, v147
	v_lshl_add_u64 v[64:65], v[66:67], 0, v[60:61]
	global_store_dword v[64:65], v55, off
	v_or_b32_e32 v54, 0x2400, v146
	v_mov_b32_e32 v55, v147
	v_lshl_add_u64 v[64:65], v[66:67], 0, v[54:55]
	global_store_dword v[64:65], v56, off
	v_or_b32_e32 v64, 0x2600, v146
	v_mov_b32_e32 v65, v147
	v_lshl_add_u64 v[62:63], v[66:67], 0, 64
	v_lshl_add_u64 v[68:69], v[66:67], 0, v[64:65]
	global_store_dword v[68:69], v57, off
	v_lshl_add_u64 v[56:57], v[62:63], 0, v[58:59]
	global_store_dword v[56:57], v46, off
	v_lshl_add_u64 v[56:57], v[62:63], 0, v[60:61]
	global_store_dword v[56:57], v47, off
	v_lshl_add_u64 v[46:47], v[62:63], 0, v[54:55]
	global_store_dword v[46:47], v48, off
	v_lshl_add_u64 v[46:47], v[62:63], 0, v[64:65]
	global_store_dword v[46:47], v49, off
	v_or_b32_e32 v46, 0x4000, v146
	v_mov_b32_e32 v47, v147
	v_lshl_add_u64 v[48:49], v[66:67], 0, v[46:47]
	global_store_dword v[48:49], v50, off
	v_or_b32_e32 v48, 0x4200, v146
	v_mov_b32_e32 v49, v147
	v_lshl_add_u64 v[54:55], v[66:67], 0, v[48:49]
	global_store_dword v[54:55], v51, off
	v_or_b32_e32 v50, 0x4400, v146
	v_mov_b32_e32 v51, v147
	v_lshl_add_u64 v[46:47], v[62:63], 0, v[46:47]
	v_lshl_add_u64 v[54:55], v[66:67], 0, v[50:51]
	global_store_dword v[46:47], v38, off
	v_lshl_add_u64 v[46:47], v[62:63], 0, v[48:49]
	global_store_dword v[54:55], v52, off
	v_or_b32_e32 v54, 0x4600, v146
	v_mov_b32_e32 v55, v147
	global_store_dword v[46:47], v39, off
	v_lshl_add_u64 v[38:39], v[62:63], 0, v[50:51]
	global_store_dword v[38:39], v40, off
	v_lshl_add_u64 v[38:39], v[62:63], 0, v[54:55]
	global_store_dword v[38:39], v41, off
	v_or_b32_e32 v38, 0x6000, v146
	v_mov_b32_e32 v39, v147
	v_lshl_add_u64 v[40:41], v[66:67], 0, v[38:39]
	global_store_dword v[40:41], v42, off
	v_or_b32_e32 v40, 0x6200, v146
	v_mov_b32_e32 v41, v147
	v_lshl_add_u64 v[46:47], v[66:67], 0, v[40:41]
	global_store_dword v[46:47], v43, off
	v_or_b32_e32 v42, 0x6400, v146
	v_mov_b32_e32 v43, v147
	v_lshl_add_u64 v[38:39], v[62:63], 0, v[38:39]
	v_lshl_add_u64 v[46:47], v[66:67], 0, v[42:43]
	global_store_dword v[38:39], v34, off
	v_lshl_add_u64 v[38:39], v[62:63], 0, v[40:41]
	global_store_dword v[46:47], v44, off
	v_or_b32_e32 v46, 0x6600, v146
	v_mov_b32_e32 v47, v147
	global_store_dword v[38:39], v35, off
	v_lshl_add_u64 v[34:35], v[62:63], 0, v[42:43]
	global_store_dword v[34:35], v36, off
	v_lshl_add_u64 v[34:35], v[62:63], 0, v[46:47]
	global_store_dword v[34:35], v37, off
	v_or_b32_e32 v34, 0x8000, v146
	v_mov_b32_e32 v35, v147
	v_lshl_add_u64 v[36:37], v[66:67], 0, v[34:35]
	global_store_dword v[36:37], v30, off
	v_or_b32_e32 v36, 0x8200, v146
	v_mov_b32_e32 v37, v147
	v_lshl_add_u64 v[38:39], v[66:67], 0, v[36:37]
	global_store_dword v[38:39], v31, off
	v_or_b32_e32 v30, 0x8400, v146
	v_mov_b32_e32 v31, v147
	v_lshl_add_u64 v[38:39], v[66:67], 0, v[30:31]
	global_store_dword v[38:39], v32, off
	v_or_b32_e32 v38, 0x8600, v146
	v_mov_b32_e32 v39, v147
	v_lshl_add_u64 v[40:41], v[66:67], 0, v[38:39]
	global_store_dword v[40:41], v33, off
	v_lshl_add_u64 v[32:33], v[62:63], 0, v[34:35]
	global_store_dword v[32:33], v22, off
	v_lshl_add_u64 v[32:33], v[62:63], 0, v[36:37]
	global_store_dword v[32:33], v23, off
	v_lshl_add_u64 v[22:23], v[62:63], 0, v[30:31]
	global_store_dword v[22:23], v24, off
	v_lshl_add_u64 v[22:23], v[62:63], 0, v[38:39]
	global_store_dword v[22:23], v25, off
	v_or_b32_e32 v22, 0xa000, v146
	v_mov_b32_e32 v23, v147
	v_lshl_add_u64 v[24:25], v[66:67], 0, v[22:23]
	global_store_dword v[24:25], v26, off
	v_or_b32_e32 v24, 0xa200, v146
	v_mov_b32_e32 v25, v147
	v_lshl_add_u64 v[30:31], v[66:67], 0, v[24:25]
	global_store_dword v[30:31], v27, off
	v_or_b32_e32 v26, 0xa400, v146
	v_mov_b32_e32 v27, v147
	v_lshl_add_u64 v[22:23], v[62:63], 0, v[22:23]
	v_lshl_add_u64 v[30:31], v[66:67], 0, v[26:27]
	global_store_dword v[22:23], v14, off
	v_lshl_add_u64 v[22:23], v[62:63], 0, v[24:25]
	global_store_dword v[30:31], v28, off
	v_or_b32_e32 v30, 0xa600, v146
	v_mov_b32_e32 v31, v147
	global_store_dword v[22:23], v15, off
	v_lshl_add_u64 v[14:15], v[62:63], 0, v[26:27]
	global_store_dword v[14:15], v16, off
	v_lshl_add_u64 v[14:15], v[62:63], 0, v[30:31]
	global_store_dword v[14:15], v17, off
	v_or_b32_e32 v14, 0xc000, v146
	v_mov_b32_e32 v15, v147
	v_lshl_add_u64 v[16:17], v[66:67], 0, v[14:15]
	global_store_dword v[16:17], v18, off
	v_or_b32_e32 v16, 0xc200, v146
	v_mov_b32_e32 v17, v147
	v_lshl_add_u64 v[22:23], v[66:67], 0, v[16:17]
	global_store_dword v[22:23], v19, off
	v_or_b32_e32 v18, 0xc400, v146
	v_mov_b32_e32 v19, v147
	v_lshl_add_u64 v[14:15], v[62:63], 0, v[14:15]
	v_lshl_add_u64 v[22:23], v[66:67], 0, v[18:19]
	global_store_dword v[14:15], v6, off
	v_lshl_add_u64 v[14:15], v[62:63], 0, v[16:17]
	global_store_dword v[22:23], v20, off
	v_or_b32_e32 v22, 0xc600, v146
	v_mov_b32_e32 v23, v147
	global_store_dword v[14:15], v7, off
	v_lshl_add_u64 v[6:7], v[62:63], 0, v[18:19]
	global_store_dword v[6:7], v8, off
	v_lshl_add_u64 v[6:7], v[62:63], 0, v[22:23]
	global_store_dword v[6:7], v9, off
	v_or_b32_e32 v6, 0xe000, v146
	v_mov_b32_e32 v7, v147
	v_lshl_add_u64 v[8:9], v[66:67], 0, v[6:7]
	global_store_dword v[8:9], v10, off
	v_or_b32_e32 v8, 0xe200, v146
	v_mov_b32_e32 v9, v147
	v_lshl_add_u64 v[14:15], v[66:67], 0, v[8:9]
	v_lshl_add_u64 v[6:7], v[62:63], 0, v[6:7]
	global_store_dword v[14:15], v11, off
	v_or_b32_e32 v10, 0xe400, v146
	v_mov_b32_e32 v11, v147
	global_store_dword v[6:7], v2, off
	v_lshl_add_u64 v[6:7], v[62:63], 0, v[8:9]
	v_lshl_add_u64 v[14:15], v[66:67], 0, v[10:11]
	v_or_b32_e32 v146, 0xe600, v146
	global_store_dword v[6:7], v3, off
	v_lshl_add_u64 v[2:3], v[62:63], 0, v[10:11]
	v_lshl_add_u64 v[56:57], v[66:67], 0, v[54:55]
	v_lshl_add_u64 v[48:49], v[66:67], 0, v[46:47]
	v_lshl_add_u64 v[32:33], v[66:67], 0, v[30:31]
	v_lshl_add_u64 v[24:25], v[66:67], 0, v[22:23]
	global_store_dword v[14:15], v12, off
	v_lshl_add_u64 v[14:15], v[66:67], 0, v[146:147]
	global_store_dword v[2:3], v4, off
	v_lshl_add_u64 v[2:3], v[62:63], 0, v[146:147]
	global_store_dword v[56:57], v53, off
	global_store_dword v[48:49], v45, off
	global_store_dword v[32:33], v29, off
	global_store_dword v[24:25], v21, off
	global_store_dword v[14:15], v13, off
	global_store_dword v[2:3], v5, off

.LBB0_1836:
	v_sub_f32_e32 v82, v82, v168
	v_exp_f32_e32 v82, v82
	v_lshrrev_b32_e32 v162, v155, v162
	v_sub_f32_e32 v66, v66, v168
	v_exp_f32_e32 v169, v66
	v_bfe_i32 v66, v162, 0, 1
	v_lshrrev_b32_e32 v163, v155, v163
	v_sub_f32_e32 v83, v83, v168
	v_exp_f32_e32 v83, v83
	v_and_b32_e32 v66, v66, v82
	v_bfe_i32 v82, v163, 0, 1
	v_sub_f32_e32 v67, v67, v168
	v_sub_f32_e32 v84, v84, v168
	v_and_b32_e32 v82, v82, v169
	v_exp_f32_e32 v169, v67
	v_bfe_i32 v67, v162, 1, 1
	v_exp_f32_e32 v84, v84
	v_sub_f32_e32 v68, v68, v168
	v_and_b32_e32 v67, v67, v83
	v_bfe_i32 v83, v163, 1, 1
	v_sub_f32_e32 v85, v85, v168
	v_exp_f32_e32 v85, v85
	v_and_b32_e32 v83, v83, v169
	v_exp_f32_e32 v169, v68
	v_bfe_i32 v68, v162, 2, 1
	v_sub_f32_e32 v69, v69, v168
	v_sub_f32_e32 v86, v86, v168
	v_and_b32_e32 v68, v68, v84
	v_bfe_i32 v84, v163, 2, 1
	v_exp_f32_e32 v86, v86
	v_sub_f32_e32 v70, v70, v168
	v_and_b32_e32 v84, v84, v169
	v_exp_f32_e32 v169, v69
	v_bfe_i32 v69, v162, 3, 1
	v_sub_f32_e32 v87, v87, v168
	v_exp_f32_e32 v87, v87
	v_and_b32_e32 v69, v69, v85
	v_bfe_i32 v85, v163, 3, 1
	v_sub_f32_e32 v71, v71, v168
	v_sub_f32_e32 v88, v88, v168
	v_and_b32_e32 v85, v85, v169
	v_exp_f32_e32 v169, v70
	v_bfe_i32 v70, v162, 8, 1
	v_exp_f32_e32 v88, v88
	v_sub_f32_e32 v72, v72, v168
	v_and_b32_e32 v70, v70, v86
	v_bfe_i32 v86, v163, 8, 1
	v_sub_f32_e32 v89, v89, v168
	v_exp_f32_e32 v89, v89
	v_and_b32_e32 v86, v86, v169
	v_exp_f32_e32 v169, v71
	v_bfe_i32 v71, v162, 9, 1
	v_sub_f32_e32 v73, v73, v168
	v_sub_f32_e32 v90, v90, v168
	v_and_b32_e32 v71, v71, v87
	v_bfe_i32 v87, v163, 9, 1
	v_exp_f32_e32 v90, v90
	v_sub_f32_e32 v74, v74, v168
	v_and_b32_e32 v87, v87, v169
	v_exp_f32_e32 v169, v72
	v_bfe_i32 v72, v162, 10, 1
	v_sub_f32_e32 v91, v91, v168
	v_exp_f32_e32 v91, v91
	v_and_b32_e32 v72, v72, v88
	v_bfe_i32 v88, v163, 10, 1
	v_sub_f32_e32 v75, v75, v168
	v_sub_f32_e32 v92, v92, v168
	v_and_b32_e32 v88, v88, v169
	v_exp_f32_e32 v169, v73
	v_bfe_i32 v73, v162, 11, 1
	v_exp_f32_e32 v92, v92
	s_mul_i32 s27, s4, 0x5000
	v_and_b32_e32 v73, v73, v89
	v_bfe_i32 v89, v163, 11, 1
	v_sub_f32_e32 v76, v76, v168
	s_add_i32 s27, s27, 0
	v_and_b32_e32 v89, v89, v169
	v_exp_f32_e32 v169, v74
	v_bfe_i32 v74, v162, 16, 1
	s_add_i32 s27, s27, 0x8800
	v_sub_f32_e32 v93, v93, v168
	v_and_b32_e32 v74, v74, v90
	v_bfe_i32 v90, v163, 16, 1
	v_add_u32_e32 v220, s27, v165
	ds_read_b64_tr_b16 v[174:175], v220 offset:0
	v_exp_f32_e32 v93, v93
	v_and_b32_e32 v90, v90, v169
	v_exp_f32_e32 v169, v75
	v_bfe_i32 v75, v162, 17, 1
	ds_read_b64_tr_b16 v[176:177], v220 offset:0xa00
	v_sub_f32_e32 v77, v77, v168
	ds_read_b64_tr_b16 v[178:179], v220 offset:0x1400
	ds_read_b64_tr_b16 v[180:181], v220 offset:0x1e00
	v_sub_f32_e32 v94, v94, v168
	v_and_b32_e32 v75, v75, v91
	v_bfe_i32 v91, v163, 17, 1
	ds_read_b64_tr_b16 v[182:183], v220 offset:0x2800
	v_exp_f32_e32 v94, v94
	ds_read_b64_tr_b16 v[184:185], v220 offset:0x3200
	v_sub_f32_e32 v78, v78, v168
	v_and_b32_e32 v91, v91, v169
	v_exp_f32_e32 v169, v76
	v_bfe_i32 v76, v162, 18, 1
	ds_read_b64_tr_b16 v[186:187], v220 offset:0x3c00
	ds_read_b64_tr_b16 v[188:189], v220 offset:0x4600
	v_sub_f32_e32 v95, v95, v168
	ds_read_b64_tr_b16 v[190:191], v220 offset:64
	v_exp_f32_e32 v95, v95
	v_and_b32_e32 v76, v76, v92
	v_bfe_i32 v92, v163, 18, 1
	ds_read_b64_tr_b16 v[192:193], v220 offset:0xa40
	v_sub_f32_e32 v79, v79, v168
	ds_read_b64_tr_b16 v[194:195], v220 offset:0x1440
	ds_read_b64_tr_b16 v[196:197], v220 offset:0x1e40
	v_sub_f32_e32 v96, v96, v168
	v_and_b32_e32 v92, v92, v169
	v_exp_f32_e32 v169, v77
	v_bfe_i32 v77, v162, 19, 1
	ds_read_b64_tr_b16 v[198:199], v220 offset:0x2840
	v_exp_f32_e32 v96, v96
	ds_read_b64_tr_b16 v[200:201], v220 offset:0x3240
	v_sub_f32_e32 v80, v80, v168
	v_and_b32_e32 v77, v77, v93
	v_bfe_i32 v93, v163, 19, 1
	ds_read_b64_tr_b16 v[204:205], v220 offset:0x3c40
	v_cvt_pk_bf16_f32 v170, v66, v67
	v_cvt_pk_bf16_f32 v171, v68, v69
	v_and_b32_e32 v93, v93, v169
	v_exp_f32_e32 v169, v78
	v_bfe_i32 v78, v162, 24, 1
	v_cvt_pk_bf16_f32 v172, v70, v71
	v_cvt_pk_bf16_f32 v173, v72, v73
	v_and_b32_e32 v78, v78, v94
	v_bfe_i32 v94, v163, 24, 1
	ds_read_b64_tr_b16 v[206:207], v220 offset:0x4640
	s_waitcnt lgkmcnt(8)
	v_sub_f32_e32 v81, v81, v168
	v_mfma_f32_32x32x16_bf16 v[50:65], v[174:177], v[170:173], v[50:65]
	v_and_b32_e32 v94, v94, v169
	v_exp_f32_e32 v169, v79
	v_bfe_i32 v79, v162, 25, 1
	v_cvt_pk_bf16_f32 v174, v74, v75
	v_cvt_pk_bf16_f32 v175, v76, v77
	v_and_b32_e32 v79, v79, v95
	v_bfe_i32 v95, v163, 25, 1
	v_cvt_pk_bf16_f32 v176, v78, v79
	v_exp_f32_e32 v81, v81
	v_and_b32_e32 v95, v95, v169
	v_exp_f32_e32 v169, v80
	v_bfe_i32 v80, v162, 26, 1
	v_bfe_i32 v208, v163, 26, 1
	s_nop 0
	v_and_b32_e32 v80, v80, v96
	v_sub_f32_e32 v96, v97, v168
	v_exp_f32_e32 v96, v96
	v_bfe_i32 v97, v162, 27, 1
	v_bfe_i32 v162, v163, 27, 1
	s_nop 0
	v_and_b32_e32 v96, v97, v96
	v_cvt_pk_bf16_f32 v177, v80, v96
	s_nop 0
	s_nop 0
	v_mfma_f32_32x32x16_bf16 v[50:65], v[178:181], v[174:177], v[50:65]
	v_cvt_pk_bf16_f32 v178, v82, v83
	v_cvt_pk_bf16_f32 v179, v84, v85
	v_cvt_pk_bf16_f32 v180, v86, v87
	v_cvt_pk_bf16_f32 v181, v88, v89
	v_and_b32_e32 v97, v208, v169
	s_nop 0
	v_mfma_f32_32x32x16_bf16 v[50:65], v[182:185], v[178:181], v[50:65]
	s_nop 0
	v_and_b32_e32 v81, v162, v81
	v_cvt_pk_bf16_f32 v182, v90, v91
	v_cvt_pk_bf16_f32 v183, v92, v93
	v_cvt_pk_bf16_f32 v184, v94, v95
	v_cvt_pk_bf16_f32 v185, v97, v81
	s_andn2_b64 vcc, exec, s[22:23]
	s_nop 0
	v_mfma_f32_32x32x16_bf16 v[50:65], v[186:189], v[182:185], v[50:65]
	ds_read_b64_tr_b16 v[186:187], v220 offset:0x80
	ds_read_b64_tr_b16 v[188:189], v220 offset:0xa80
	ds_read_b64_tr_b16 v[208:209], v220 offset:0x1480
	ds_read_b64_tr_b16 v[210:211], v220 offset:0x1e80
	ds_read_b64_tr_b16 v[212:213], v220 offset:0x2880
	ds_read_b64_tr_b16 v[214:215], v220 offset:0x3280
	ds_read_b64_tr_b16 v[216:217], v220 offset:0x3c80
	ds_read_b64_tr_b16 v[218:219], v220 offset:0x4680
	s_waitcnt lgkmcnt(8)
	s_nop 0
	v_mfma_f32_32x32x16_bf16 v[34:49], v[190:193], v[170:173], v[34:49]
	ds_read_b64_tr_b16 v[190:191], v220 offset:0xc0
	ds_read_b64_tr_b16 v[192:193], v220 offset:0xac0
	v_mfma_f32_32x32x16_bf16 v[34:49], v[194:197], v[174:177], v[34:49]
	ds_read_b64_tr_b16 v[194:195], v220 offset:0x14c0
	ds_read_b64_tr_b16 v[196:197], v220 offset:0x1ec0
	v_mfma_f32_32x32x16_bf16 v[34:49], v[198:201], v[178:181], v[34:49]
	ds_read_b64_tr_b16 v[198:199], v220 offset:0x28c0
	ds_read_b64_tr_b16 v[200:201], v220 offset:0x32c0
	v_mfma_f32_32x32x16_bf16 v[34:49], v[204:207], v[182:185], v[34:49]
	ds_read_b64_tr_b16 v[204:205], v220 offset:0x3cc0
	ds_read_b64_tr_b16 v[206:207], v220 offset:0x46c0
	s_waitcnt lgkmcnt(8)
	s_nop 0
	s_waitcnt lgkmcnt(0)
	v_mfma_f32_32x32x16_bf16 v[18:33], v[186:189], v[170:173], v[18:33]
	v_mfma_f32_32x32x16_bf16 v[2:17], v[190:193], v[170:173], v[2:17]
	v_mfma_f32_32x32x16_bf16 v[18:33], v[208:211], v[174:177], v[18:33]
	v_mfma_f32_32x32x16_bf16 v[2:17], v[194:197], v[174:177], v[2:17]
	v_mfma_f32_32x32x16_bf16 v[18:33], v[212:215], v[178:181], v[18:33]
	v_mfma_f32_32x32x16_bf16 v[2:17], v[198:201], v[178:181], v[2:17]
	v_mfma_f32_32x32x16_bf16 v[18:33], v[216:219], v[182:185], v[18:33]
	v_mfma_f32_32x32x16_bf16 v[2:17], v[204:207], v[182:185], v[2:17]
	s_cbranch_vccnz .LBB0_1838
	s_xor_b32 s4, s4, 1
	s_mul_i32 s22, s4, 0x4400
	s_mulk_i32 s4, 0x5000
	v_add_u32_e32 v162, s22, v152
	s_waitcnt vmcnt(1)
	ds_write_b128 v162, v[102:105]
	ds_write_b128 v162, v[98:101] offset:16
	v_add_u32_e32 v162, s4, v154
	ds_write_b128 v162, v[106:109] offset:34816
	s_waitcnt vmcnt(0)
	ds_write_b128 v162, v[118:121] offset:34832
